# MLA mid phase: next row's loads and rope-table pair issued one iteration ahead (one exposed round trip per row instead of two)
# baseline (speedup 1.0000x reference)
.LBB0_616:
	s_and_b64 vcc, exec, s[6:7]
	s_cbranch_vccz .LBB0_632
	v_mov_b32_e32 v6, v249
	v_readlane_b32 s0, v252, 58
	v_ashrrev_i32_e32 v0, 6, v6
	s_nop 0
	v_add_u32_e32 v10, s0, v0
	v_cmp_gt_i32_e32 vcc, s9, v10
	s_and_saveexec_b64 s[6:7], vcc
	v_readlane_b32 s0, v252, 59
	s_cbranch_execz .LBB0_631
	v_and_b32_e32 v12, 63, v6
	s_mov_b64 s[2:3], s[52:53]
	v_readlane_b32 s40, v254, 18
	v_lshlrev_b32_e32 v0, 4, v12
	v_readlane_b32 s46, v254, 24
	v_readlane_b32 s47, v254, 25
	v_readlane_b32 s20, v254, 10
	v_lshlrev_b32_e32 v8, 3, v12
	v_readlane_b32 s21, v254, 11
	v_readlane_b32 s22, v254, 12
	v_readlane_b32 s23, v254, 13
	global_load_dwordx4 v[2:5], v0, s[46:47]
	v_and_b32_e32 v0, 31, v6
	v_lshlrev_b32_e32 v0, 2, v0
	global_load_dwordx2 v[14:15], v8, s[20:21]
	v_and_b32_e32 v7, 64, v212
	global_load_dword v13, v0, s[22:23]
	v_add_u32_e32 v7, 64, v7
	v_xor_b32_e32 v11, 1, v212
	v_cmp_lt_i32_e32 vcc, v11, v7
	v_readlane_b32 s52, v254, 30
	v_readlane_b32 s53, v254, 31
	v_cndmask_b32_e32 v11, v212, v11, vcc
	v_lshlrev_b32_e32 v30, 2, v11
	v_xor_b32_e32 v11, 2, v212
	v_cmp_lt_i32_e32 vcc, v11, v7
	s_mov_b64 s[52:53], s[2:3]
	v_readlane_b32 s2, v252, 52
	v_cndmask_b32_e32 v11, v212, v11, vcc
	v_lshlrev_b32_e32 v31, 2, v11
	v_xor_b32_e32 v11, 4, v212
	v_cmp_lt_i32_e32 vcc, v11, v7
	v_mov_b32_e32 v9, v1
	v_readlane_b32 s3, v252, 53
	v_cndmask_b32_e32 v11, v212, v11, vcc
	v_lshlrev_b32_e32 v32, 2, v11
	v_xor_b32_e32 v11, 8, v212
	v_cmp_lt_i32_e32 vcc, v11, v7
	v_lshl_add_u64 v[16:17], s[2:3], 0, v[8:9]
	v_readlane_b32 s2, v252, 54
	v_cndmask_b32_e32 v11, v212, v11, vcc
	v_lshlrev_b32_e32 v33, 2, v11
	v_xor_b32_e32 v11, 16, v212
	v_cmp_lt_i32_e32 vcc, v11, v7
	v_lshlrev_b32_e32 v0, 2, v12
	v_readlane_b32 s3, v252, 55
	v_cndmask_b32_e32 v11, v212, v11, vcc
	v_lshlrev_b32_e32 v34, 2, v11
	v_xor_b32_e32 v11, 32, v212
	v_lshl_add_u64 v[18:19], s[2:3], 0, v[0:1]
	v_cmp_lt_i32_e32 vcc, v11, v7
	v_readlane_b32 s2, v252, 36
	v_lshlrev_b32_e32 v24, 1, v12
	v_mov_b32_e32 v25, v1
	v_cndmask_b32_e32 v7, v212, v11, vcc
	v_readlane_b32 s3, v252, 37
	v_readlane_b32 s41, v254, 19
	v_lshlrev_b32_e32 v35, 2, v7
	v_and_b32_e32 v7, 16, v6
	v_lshl_add_u64 v[20:21], s[2:3], 0, v[24:25]
	v_readlane_b32 s2, v252, 60
	v_readlane_b32 s42, v254, 20
	v_readlane_b32 s43, v254, 21
	v_cmp_eq_u32_e64 s[40:41], 0, v7
	v_and_b32_e32 v7, 7, v6
	v_and_b32_e32 v6, 8, v6
	v_readlane_b32 s3, v252, 61
	v_cmp_gt_u32_e64 s[38:39], 32, v12
	v_cmp_eq_u32_e64 s[42:43], 0, v6
	v_lshl_add_u64 v[22:23], s[2:3], 0, v[8:9]
	s_mov_b64 s[20:21], 0
	v_lshlrev_b32_e32 v0, 2, v0
	v_lshlrev_b32_e32 v24, 2, v24
	v_lshlrev_b32_e32 v36, 2, v7
	v_readlane_b32 s44, v254, 22
	v_readlane_b32 s45, v254, 23
	v_readlane_b32 s48, v254, 26
	v_readlane_b32 s49, v254, 27
	v_readlane_b32 s50, v254, 28
	v_readlane_b32 s51, v254, 29
	v_readlane_b32 s54, v254, 32
	v_readlane_b32 s55, v254, 33
	v_readlane_b32 s24, v254, 14
	v_readlane_b32 s25, v254, 15
	v_readlane_b32 s26, v254, 16
	v_readlane_b32 s27, v254, 17
	v_mov_b32_e32 v58, v10
	v_mov_b32_e32 v59, 0
	v_readlane_b32 s2, v252, 22
	v_readlane_b32 s3, v252, 23
	v_lshlrev_b64 v[52:53], 11, v[58:59]
	s_nop 0
	v_lshl_add_u64 v[60:61], s[2:3], 0, v[52:53]
	v_lshl_add_u64 v[52:53], v[60:61], 0, v[0:1]
	global_load_dwordx4 v[44:47], v[52:53], off
	v_mov_b32_e32 v62, v24
	v_mov_b32_e32 v63, 0
	v_lshl_add_u64 v[52:53], v[60:61], 0, v[62:63]
	global_load_dwordx2 v[48:49], v[52:53], off offset:1024
	v_mov_b32_e32 v50, 0
	s_and_saveexec_b64 s[22:23], s[38:39]
	v_lshlrev_b32_e32 v52, 2, v12
	v_mov_b32_e32 v53, 0
	v_lshl_add_u64 v[52:53], v[60:61], 0, v[52:53]
	global_load_dword v50, v[52:53], off offset:1536
	s_mov_b64 exec, s[22:23]
	v_and_b32_e32 v52, 63, v58
	v_bfe_u32 v53, v58, 6, 5
	v_cndmask_b32_e64 v52, v52, v53, s[40:41]
	v_readlane_b32 s2, v252, 56
	v_readlane_b32 s3, v252, 57
	v_lshl_or_b32 v52, v52, 5, v36
	v_mov_b32_e32 v53, 0
	v_lshl_add_u64 v[52:53], s[2:3], 0, v[52:53]
	v_mov_b32_e32 v60, 0x2000
	v_mov_b32_e32 v61, 0
	v_lshl_add_u64 v[52:53], v[52:53], 0, v[60:61]
	global_load_dword v56, v[52:53], off
	global_load_dword v57, v[52:53], off offset:2048
	s_waitcnt vmcnt(0)
	s_branch .Lmm_enter

.LBB0_620:
	s_waitcnt vmcnt(2)
.Lmm_enter:
	v_ashrrev_i32_e32 v11, 31, v10
	v_mov_b32_e32 v6, v44
	v_mov_b32_e32 v7, v45
	v_mov_b32_e32 v8, v46
	v_mov_b32_e32 v9, v47
	v_mov_b32_e32 v26, v48
	v_mov_b32_e32 v27, v49
	v_mov_b32_e32 v25, v50
	v_mov_b32_e32 v54, v56
	v_mov_b32_e32 v55, v57
	v_add_u32_e32 v58, s0, v10
	v_cmp_ge_i32_e32 vcc, s68, v58
	s_and_b64 vcc, exec, vcc
	s_cbranch_vccz .Lmm_nopf
	v_mov_b32_e32 v59, 0
	v_readlane_b32 s2, v252, 22
	v_readlane_b32 s3, v252, 23
	v_lshlrev_b64 v[52:53], 11, v[58:59]
	s_nop 0
	v_lshl_add_u64 v[60:61], s[2:3], 0, v[52:53]
	v_lshl_add_u64 v[52:53], v[60:61], 0, v[0:1]
	global_load_dwordx4 v[44:47], v[52:53], off
	v_mov_b32_e32 v62, v24
	v_mov_b32_e32 v63, 0
	v_lshl_add_u64 v[52:53], v[60:61], 0, v[62:63]
	global_load_dwordx2 v[48:49], v[52:53], off offset:1024
	v_mov_b32_e32 v50, 0
	s_and_saveexec_b64 s[22:23], s[38:39]
	v_lshlrev_b32_e32 v52, 2, v12
	v_mov_b32_e32 v53, 0
	v_lshl_add_u64 v[52:53], v[60:61], 0, v[52:53]
	global_load_dword v50, v[52:53], off offset:1536
	s_mov_b64 exec, s[22:23]
	v_and_b32_e32 v52, 63, v58
	v_bfe_u32 v53, v58, 6, 5
	v_cndmask_b32_e64 v52, v52, v53, s[40:41]
	v_readlane_b32 s2, v252, 56
	v_readlane_b32 s3, v252, 57
	v_lshl_or_b32 v52, v52, 5, v36
	v_mov_b32_e32 v53, 0
	v_lshl_add_u64 v[52:53], s[2:3], 0, v[52:53]
	v_mov_b32_e32 v60, 0x2000
	v_mov_b32_e32 v61, 0
	v_lshl_add_u64 v[52:53], v[52:53], 0, v[60:61]
	global_load_dword v56, v[52:53], off
	global_load_dword v57, v[52:53], off offset:2048
.Lmm_nopf:
	v_pk_mul_f32 v[28:29], v[8:9], v[8:9]
	v_pk_mul_f32 v[38:39], v[6:7], v[6:7]
	s_mov_b32 s2, 0x3d000000
	v_pk_mov_b32 v[40:41], v[38:39], v[28:29] op_sel:[1,0]
	v_mov_b32_e32 v39, v29
	v_pk_add_f32 v[28:29], v[40:41], v[38:39]
	v_mul_f32_e32 v40, v25, v25
	v_add_f32_e32 v28, v28, v29
	ds_bpermute_b32 v29, v30, v28
	ds_bpermute_b32 v38, v30, v40
	s_brev_b32 s3, 60
	s_mov_b64 s[22:23], 0
	s_waitcnt lgkmcnt(0)
	v_add_f32_e32 v28, v28, v29
	ds_bpermute_b32 v29, v31, v28
	s_waitcnt lgkmcnt(0)
	v_add_f32_e32 v28, v28, v29
	ds_bpermute_b32 v29, v32, v28
	s_waitcnt lgkmcnt(0)
	v_add_f32_e32 v28, v28, v29
	ds_bpermute_b32 v29, v33, v28
	s_waitcnt lgkmcnt(0)
	v_add_f32_e32 v28, v28, v29
	ds_bpermute_b32 v29, v34, v28
	s_waitcnt lgkmcnt(0)
	v_add_f32_e32 v28, v28, v29
	ds_bpermute_b32 v29, v35, v28
	s_waitcnt lgkmcnt(0)
	v_add_f32_e32 v37, v28, v29
	v_mul_f32_e32 v28, v27, v27
	v_pk_fma_f32 v[28:29], v[26:27], v[26:27], v[28:29] op_sel_hi:[1,1,0]
	ds_bpermute_b32 v39, v30, v28
	v_fmamk_f32 v29, v37, 0x3b800000, v248
	v_cmp_gt_f32_e32 vcc, s8, v29
	v_mul_f32_e32 v37, 0x4b800000, v29
	v_mov_b32_e32 v41, v28
	v_cndmask_b32_e32 v29, v29, v37, vcc
	v_rsq_f32_e32 v29, v29
	s_nop 0
	v_mul_f32_e32 v37, 0x45800000, v29
	v_cndmask_b32_e32 v42, v29, v37, vcc
	s_waitcnt lgkmcnt(0)
	v_pk_add_f32 v[28:29], v[40:41], v[38:39]
	ds_bpermute_b32 v39, v31, v29
	ds_bpermute_b32 v38, v31, v28
	v_pk_mul_f32 v[6:7], v[6:7], v[42:43] op_sel_hi:[1,0]
	v_pk_mul_f32 v[8:9], v[8:9], v[42:43] op_sel_hi:[1,0]
	v_pk_mul_f32 v[6:7], v[2:3], v[6:7]
	v_pk_mul_f32 v[8:9], v[4:5], v[8:9]
	s_waitcnt lgkmcnt(0)
	v_pk_add_f32 v[28:29], v[28:29], v[38:39]
	ds_bpermute_b32 v39, v32, v29
	ds_bpermute_b32 v38, v32, v28
	v_cvt_pk_bf16_f32 v6, v6, v7
	v_cvt_pk_bf16_f32 v7, v8, v9
	v_lshlrev_b64 v[8:9], 9, v[10:11]
	v_lshl_add_u64 v[8:9], v[16:17], 0, v[8:9]
	s_waitcnt lgkmcnt(0)
	v_pk_add_f32 v[28:29], v[28:29], v[38:39]
	ds_bpermute_b32 v39, v33, v29
	ds_bpermute_b32 v38, v33, v28
	global_store_dwordx2 v[8:9], v[6:7], off
	v_lshlrev_b64 v[8:9], 8, v[10:11]
	v_lshl_add_u64 v[8:9], v[18:19], 0, v[8:9]
	s_waitcnt lgkmcnt(0)
	v_pk_add_f32 v[28:29], v[28:29], v[38:39]
	ds_bpermute_b32 v39, v34, v29
	ds_bpermute_b32 v38, v34, v28
	s_waitcnt lgkmcnt(0)
	v_pk_add_f32 v[28:29], v[28:29], v[38:39]
	ds_bpermute_b32 v39, v35, v29
	ds_bpermute_b32 v38, v35, v28
	s_waitcnt lgkmcnt(0)
	v_pk_add_f32 v[28:29], v[28:29], v[38:39]
	s_nop 0
	v_pk_fma_f32 v[28:29], v[28:29], s[2:3], v[248:249] op_sel_hi:[1,1,0]
	s_movk_i32 s2, 0x1fff
	v_mul_f32_e32 v37, 0x4b800000, v29
	v_cmp_gt_f32_e64 s[44:45], s8, v29
	v_cmp_gt_f32_e32 vcc, s8, v28
	s_nop 0
	v_cndmask_b32_e64 v29, v29, v37, s[44:45]
	v_rsq_f32_e32 v29, v29
	s_nop 0
	v_mul_f32_e32 v37, 0x45800000, v29
	v_cndmask_b32_e64 v38, v29, v37, s[44:45]
	v_mul_f32_e32 v29, 0x4b800000, v28
	v_cndmask_b32_e32 v28, v28, v29, vcc
	v_rsq_f32_e32 v28, v28
	v_pk_mul_f32 v[6:7], v[26:27], v[38:39] op_sel_hi:[1,0]
	v_mul_f32_e32 v29, 0x45800000, v28
	v_pk_mul_f32 v[6:7], v[14:15], v[6:7]
	v_cndmask_b32_e32 v28, v28, v29, vcc
	v_cvt_pk_bf16_f32 v26, v6, v7
	global_store_dword v[8:9], v26, off
	v_mul_f32_e32 v8, v25, v28
	v_mul_f32_e32 v25, v13, v8
	v_cmp_lt_i32_e32 vcc, s2, v10
	s_and_saveexec_b64 s[10:11], vcc
	s_xor_b64 s[44:45], exec, s[10:11]
	s_cbranch_execz .LBB0_625
	s_mov_b64 s[22:23], exec
	v_mov_b32_e32 v9, v54
	v_mov_b32_e32 v6, v55
	ds_bpermute_b32 v7, v33, v25
	s_waitcnt lgkmcnt(0)
	v_mul_f32_e32 v6, v6, v7
	v_cndmask_b32_e64 v8, v6, -v6, s[42:43]
	v_fmac_f32_e32 v8, v25, v9
	s_andn2_saveexec_b64 s[44:45], s[44:45]
	s_cbranch_execnz .LBB0_626
